# grid barrier: XCD leader bumps the per-XCD generation before its own vmcnt(0)+buffer_inv (byte-neutral)
# speedup vs baseline: 1.0024x; 1.0005x over previous
; DI unsigned xb_add(unsigned* p, unsigned v) { return __hip_atomic_fetch_add(p, v, __ATOMIC_RELAXED, __HIP_MEMORY_SCOPE_AGENT); }
; DI void xcd_barrier(const XcdBarrier& b) {
;     ...
;       __builtin_amdgcn_fence(__ATOMIC_ACQUIRE, "agent");
;       xb_add(&bar[XB_XGEN(b.x)], 1u);
;       asm volatile("s_waitcnt vmcnt(0)" ::: "memory");
.LBB0_161:
	s_or_b64 exec, exec, s[2:3]
	s_mov_b64 s[2:3], exec
	v_mbcnt_lo_u32_b32 v0, s2, 0
	v_mbcnt_hi_u32_b32 v0, s3, v0
	v_cmp_eq_u32_e32 vcc, 0, v0
	s_nop 0
	s_and_saveexec_b64 s[4:5], vcc
	s_cbranch_execz .LBB0_163
	s_bcnt1_i32_b64 s2, s[2:3]
	v_mov_b32_e32 v1, s2
	v_readlane_b32 s2, v254, 34
	v_mov_b32_e32 v0, 0
	v_readlane_b32 s3, v254, 35
	s_nop 4
	global_atomic_add v0, v1, s[2:3]
.LBB0_163:
	s_or_b64 exec, exec, s[4:5]
	buffer_inv sc1
	s_waitcnt vmcnt(0)

; DI unsigned xb_add(unsigned* p, unsigned v) { return __hip_atomic_fetch_add(p, v, __ATOMIC_RELAXED, __HIP_MEMORY_SCOPE_AGENT); }
; DI void xcd_barrier(const XcdBarrier& b) {
;     ...
;       __builtin_amdgcn_fence(__ATOMIC_ACQUIRE, "agent");
;       xb_add(&bar[XB_XGEN(b.x)], 1u);
;       asm volatile("s_waitcnt vmcnt(0)" ::: "memory");
.LBB0_257:
	s_or_b64 exec, exec, s[2:3]
	s_mov_b64 s[2:3], exec
	v_mbcnt_lo_u32_b32 v0, s2, 0
	v_mbcnt_hi_u32_b32 v0, s3, v0
	v_cmp_eq_u32_e32 vcc, 0, v0
	s_nop 0
	s_and_saveexec_b64 s[4:5], vcc
	s_cbranch_execz .LBB0_259
	s_bcnt1_i32_b64 s2, s[2:3]
	v_mov_b32_e32 v0, s2
	v_readlane_b32 s2, v254, 34
	v_readlane_b32 s3, v254, 35
	s_nop 4
	global_atomic_add v1, v0, s[2:3]
